# MLA item output: 8 dwordx2 stores (16 B runs) -> 4 dwordx4 stores writing whole 128 B lines after a 3-stage lane transpose (permlane32_swap, DPP row_ror:8, permlane16_swap)
# speedup vs baseline: 1.0207x; 1.0014x over previous
; DI u32x2 pack4(const float* v) { u32x2 w; w.x = pk2(v[0], v[1]); w.y = pk2(v[2], v[3]); return w; }
; DI float shx(float v, int lane, int m) { return __builtin_bit_cast(float, __builtin_amdgcn_ds_bpermute((lane ^ m) << 2, __builtin_bit_cast(int, v))); }
; DI void mla_item(int g_wave, LAS unsigned char* lds, const bf16_t* QN, const bf16_t* QR, const bf16_t* KN, const bf16_t* KRb, const bf16_t* VM, bf16_t* MIX,
;                  int kvbase, int qrow0, int nq, int head, int ntiles, int wt) {
;     ...
;     if (active) {
;         const float lt = l_run + shx(l_run, lane, 32), inv = 1.f / lt;
;         bf16_t* orow_ = MIX + (size_t)(qrow0 + 32 * w + r) * 1024 + head * 64;
; #pragma unroll
;         for (int g = 0; g < 4; ++g) {
;             float a[4], b[4];
; #pragma unroll
;             for (int j = 0; j < 4; ++j) { a[j] = o0[4 * g + j] * inv; b[j] = o1[4 * g + j] * inv; }
;             *(u32x2*)(orow_ + 8 * g + 4 * h) = pack4(a);
;             *(u32x2*)(orow_ + 32 + 8 * g + 4 * h) = pack4(b);
;         }
;     }
.LBB0_1018:
	s_or_b64 exec, exec, s[0:1]
	s_waitcnt lgkmcnt(0)
	s_barrier
	s_and_b64 vcc, exec, s[2:3]
	s_cbranch_vccz .LBB0_887
	ds_bpermute_b32 v34, v103, v115
	v_mbcnt_lo_u32_b32 v36, -1, 0
	v_mbcnt_hi_u32_b32 v36, -1, v36
	v_add_u32_e32 v32, s10, v114
	v_and_b32_e32 v37, 24, v36
	v_sub_u32_e32 v32, v32, v37
	v_ashrrev_i32_e32 v33, 31, v32
	v_lshlrev_b64 v[32:33], 11, v[32:33]
	v_lshl_add_u64 v[32:33], s[42:43], 0, v[32:33]
	v_lshl_add_u64 v[32:33], s[92:93], 1, v[32:33]
	v_bfe_u32 v37, v36, 4, 1
	v_lshlrev_b32_e32 v37, 6, v37
	v_bfe_u32 v38, v36, 3, 1
	v_lshl_add_u32 v37, v38, 5, v37
	v_lshrrev_b32_e32 v38, 5, v36
	v_lshl_add_u32 v224, v38, 4, v37
	v_lshl_add_u64 v[32:33], v[32:33], 0, v[224:225]
	s_waitcnt lgkmcnt(0)
	v_add_f32_e32 v34, v115, v34
	v_div_scale_f32 v35, s[0:1], v34, v34, 1.0
	v_rcp_f32_e32 v36, v35
	v_div_scale_f32 v37, vcc, 1.0, v34, 1.0
	v_fma_f32 v38, -v35, v36, 1.0
	v_fmac_f32_e32 v36, v38, v36
	v_mul_f32_e32 v38, v37, v36
	v_fma_f32 v39, -v35, v38, v37
	v_fmac_f32_e32 v38, v39, v36
	v_fma_f32 v35, -v35, v38, v37
	v_div_fmas_f32 v35, v35, v36, v38
	v_div_fixup_f32 v34, v35, v34, 1.0
	v_pk_mul_f32 v[0:1], v[0:1], v[34:35] op_sel_hi:[1,0]
	v_pk_mul_f32 v[2:3], v[2:3], v[34:35] op_sel_hi:[1,0]
	v_pk_mul_f32 v[4:5], v[4:5], v[34:35] op_sel_hi:[1,0]
	v_pk_mul_f32 v[6:7], v[6:7], v[34:35] op_sel_hi:[1,0]
	v_pk_mul_f32 v[8:9], v[8:9], v[34:35] op_sel_hi:[1,0]
	v_pk_mul_f32 v[10:11], v[10:11], v[34:35] op_sel_hi:[1,0]
	v_pk_mul_f32 v[12:13], v[12:13], v[34:35] op_sel_hi:[1,0]
	v_pk_mul_f32 v[14:15], v[14:15], v[34:35] op_sel_hi:[1,0]
	v_pk_mul_f32 v[16:17], v[16:17], v[34:35] op_sel_hi:[1,0]
	v_pk_mul_f32 v[18:19], v[18:19], v[34:35] op_sel_hi:[1,0]
	v_pk_mul_f32 v[20:21], v[20:21], v[34:35] op_sel_hi:[1,0]
	v_pk_mul_f32 v[22:23], v[22:23], v[34:35] op_sel_hi:[1,0]
	v_pk_mul_f32 v[24:25], v[24:25], v[34:35] op_sel_hi:[1,0]
	v_pk_mul_f32 v[26:27], v[26:27], v[34:35] op_sel_hi:[1,0]
	v_pk_mul_f32 v[28:29], v[28:29], v[34:35] op_sel_hi:[1,0]
	v_pk_mul_f32 v[30:31], v[30:31], v[34:35] op_sel_hi:[1,0]
	v_cvt_pk_bf16_f32 v0, v0, v1
	v_cvt_pk_bf16_f32 v1, v2, v3
	v_cvt_pk_bf16_f32 v2, v4, v5
	v_cvt_pk_bf16_f32 v3, v6, v7
	v_cvt_pk_bf16_f32 v4, v8, v9
	v_cvt_pk_bf16_f32 v5, v10, v11
	v_cvt_pk_bf16_f32 v6, v12, v13
	v_cvt_pk_bf16_f32 v7, v14, v15
	v_cvt_pk_bf16_f32 v8, v16, v17
	v_cvt_pk_bf16_f32 v9, v18, v19
	v_cvt_pk_bf16_f32 v10, v20, v21
	v_cvt_pk_bf16_f32 v11, v22, v23
	v_cvt_pk_bf16_f32 v12, v24, v25
	v_cvt_pk_bf16_f32 v13, v26, v27
	v_cvt_pk_bf16_f32 v14, v28, v29
	v_cvt_pk_bf16_f32 v15, v30, v31
	s_nop 1
	v_permlane32_swap_b32_e32 v0, v2
	v_permlane32_swap_b32_e32 v1, v3
	v_permlane32_swap_b32_e32 v4, v6
	v_permlane32_swap_b32_e32 v5, v7
	v_permlane32_swap_b32_e32 v8, v10
	v_permlane32_swap_b32_e32 v9, v11
	v_permlane32_swap_b32_e32 v12, v14
	v_permlane32_swap_b32_e32 v13, v15
	v_mov_b32_e32 v16, v4
	v_mov_b32_e32 v17, v5
	v_mov_b32_e32 v18, v6
	v_mov_b32_e32 v19, v7
	v_mov_b32_e32 v20, v12
	v_mov_b32_e32 v21, v13
	v_mov_b32_e32 v22, v14
	v_mov_b32_e32 v23, v15
	s_nop 1
	v_mov_b32_dpp v4, v0 row_ror:8 row_mask:0xf bank_mask:0x3
	v_mov_b32_dpp v5, v1 row_ror:8 row_mask:0xf bank_mask:0x3
	v_mov_b32_dpp v6, v2 row_ror:8 row_mask:0xf bank_mask:0x3
	v_mov_b32_dpp v7, v3 row_ror:8 row_mask:0xf bank_mask:0x3
	v_mov_b32_dpp v12, v8 row_ror:8 row_mask:0xf bank_mask:0x3
	v_mov_b32_dpp v13, v9 row_ror:8 row_mask:0xf bank_mask:0x3
	v_mov_b32_dpp v14, v10 row_ror:8 row_mask:0xf bank_mask:0x3
	v_mov_b32_dpp v15, v11 row_ror:8 row_mask:0xf bank_mask:0x3
	v_mov_b32_dpp v0, v16 row_ror:8 row_mask:0xf bank_mask:0xc
	v_mov_b32_dpp v1, v17 row_ror:8 row_mask:0xf bank_mask:0xc
	v_mov_b32_dpp v2, v18 row_ror:8 row_mask:0xf bank_mask:0xc
	v_mov_b32_dpp v3, v19 row_ror:8 row_mask:0xf bank_mask:0xc
	v_mov_b32_dpp v8, v20 row_ror:8 row_mask:0xf bank_mask:0xc
	v_mov_b32_dpp v9, v21 row_ror:8 row_mask:0xf bank_mask:0xc
	v_mov_b32_dpp v10, v22 row_ror:8 row_mask:0xf bank_mask:0xc
	v_mov_b32_dpp v11, v23 row_ror:8 row_mask:0xf bank_mask:0xc
	s_nop 1
	v_permlane16_swap_b32_e32 v0, v8
	v_permlane16_swap_b32_e32 v1, v9
	v_permlane16_swap_b32_e32 v2, v10
	v_permlane16_swap_b32_e32 v3, v11
	v_permlane16_swap_b32_e32 v4, v12
	v_permlane16_swap_b32_e32 v5, v13
	v_permlane16_swap_b32_e32 v6, v14
	v_permlane16_swap_b32_e32 v7, v15
	s_nop 1
	global_store_dwordx4 v[32:33], v[0:3], off
	v_add_co_u32_e32 v32, vcc, 0x4000, v32
	s_nop 1
	v_addc_co_u32_e32 v33, vcc, 0, v33, vcc
	global_store_dwordx4 v[32:33], v[4:7], off
	v_add_co_u32_e32 v32, vcc, 0x4000, v32
	s_nop 1
	v_addc_co_u32_e32 v33, vcc, 0, v33, vcc
	global_store_dwordx4 v[32:33], v[8:11], off
	v_add_co_u32_e32 v32, vcc, 0x4000, v32
	s_nop 1
	v_addc_co_u32_e32 v33, vcc, 0, v33, vcc
	global_store_dwordx4 v[32:33], v[12:15], off
	s_branch .LBB0_887
